# deferred weight transposes split: 9 units per block in mixer pass-1 job loop, rest in pass-2 GLA job loop (layer 0)
# baseline (speedup 1.0000x reference)
.Ldt0_nrot:
	s_addk_i32 s52, 0xa08
	s_mul_i32 s9, s84, 9
	s_addk_i32 s9, 0xa08
	s_min_u32 s9, s9, 0x1c10
	s_cmp_ge_u32 s52, s9
	s_cbranch_scc1 .Ldt0_skip
	s_waitcnt lgkmcnt(0)
	s_barrier
	v_readlane_b32 s54, v254, 54
	v_readlane_b32 s55, v254, 55
	v_readlane_b32 s56, v253, 2
	v_readlane_b32 s57, v253, 3
	v_readlane_b32 s58, v253, 8
	v_readlane_b32 s59, v253, 9
	v_readlane_b32 s60, v253, 10
	v_readlane_b32 s61, v253, 11
	v_readlane_b32 s62, v254, 12
	v_readlane_b32 s63, v254, 13
	v_and_b32_e32 v106, 7, v180
	v_lshrrev_b32_e32 v93, 3, v180
	s_add_u32 s54, s54, 0xa080000
	s_addc_u32 s55, s55, 0
	s_add_u32 s58, s58, 0x5000000
	s_addc_u32 s59, s59, 0
	s_add_u32 s60, s60, 0x40000
	s_addc_u32 s61, s61, 0
	v_lshlrev_b32_e32 v94, 4, v106
	v_bfe_u32 v107, v180, 3, 1
	v_lshlrev_b32_e32 v108, 2, v106
	v_lshl_add_u32 v108, v107, 1, v108
	v_mul_u32_u24_e32 v84, 0x410, v108
	v_lshrrev_b32_e32 v109, 3, v93
	v_xor_b32_e32 v109, v109, v106
	v_lshlrev_b32_e32 v109, 3, v109
	v_and_b32_e32 v110, 6, v93
	v_or_b32_e32 v109, v109, v110
	v_lshl_add_u32 v84, v109, 1, v84
	v_cmp_ne_u32_e64 s[74:75], 0, v107
	v_mov_b32_e32 v104, 0x1000504
	v_mov_b32_e32 v105, 0x3020706
	v_mov_b32_e32 v111, 0x5040100
	v_mov_b32_e32 v112, 0x7060302
	v_cndmask_b32_e64 v104, v104, v111, s[74:75]
	v_cndmask_b32_e64 v105, v105, v112, s[74:75]
	v_lshrrev_b32_e32 v106, 6, v180
	v_and_b32_e32 v107, 63, v180
	v_lshrrev_b32_e32 v108, 2, v106
	v_add_u32_e32 v109, 0, v108
	v_xor_b32_e32 v109, v109, v107
	v_lshlrev_b32_e32 v109, 4, v109
	v_add_u32_e32 v110, 0, v106
	v_mul_u32_u24_e32 v110, 0x410, v110
	v_add_u32_e32 v85, v109, v110
	v_add_u32_e32 v109, 2, v108
	v_xor_b32_e32 v109, v109, v107
	v_lshlrev_b32_e32 v109, 4, v109
	v_add_u32_e32 v110, 8, v106
	v_mul_u32_u24_e32 v110, 0x410, v110
	v_add_u32_e32 v86, v109, v110
	v_add_u32_e32 v109, 4, v108
	v_xor_b32_e32 v109, v109, v107
	v_lshlrev_b32_e32 v109, 4, v109
	v_add_u32_e32 v110, 16, v106
	v_mul_u32_u24_e32 v110, 0x410, v110
	v_add_u32_e32 v87, v109, v110
	v_add_u32_e32 v109, 6, v108
	v_xor_b32_e32 v109, v109, v107
	v_lshlrev_b32_e32 v109, 4, v109
	v_add_u32_e32 v110, 24, v106
	v_mul_u32_u24_e32 v110, 0x410, v110
	v_add_u32_e32 v88, v109, v110
	v_lshlrev_b32_e32 v109, 13, v106
	v_lshl_add_u32 v89, v107, 4, v109
	v_add_u32_e32 v90, 0x10000, v89
	v_add_u32_e32 v91, 0x20000, v89
	v_add_u32_e32 v92, 0x30000, v89
	s_mov_b32 s53, 0
	s_mov_b32 s73, 0
	s_cmpk_ge_u32 s52, 0x1410
	s_cbranch_scc1 .Ldt0_out0
	s_sub_i32 s0, s52, 0xa08
	s_mul_i32 s1, s0, 0xcc3
	s_lshr_b32 s1, s1, 20
	s_mul_i32 s2, s1, 0x141
	s_sub_u32 s2, s0, s2
	s_lshl_b32 s3, s2, 7
	s_mul_i32 s4, s1, 0x1410000
	s_add_u32 s3, s3, s4
	s_add_u32 s64, s54, s3
	s_addc_u32 s65, s55, 0
	s_mov_b32 s7, 0xa080
	s_lshl_b32 s4, s1, 10
	s_cmpk_lt_u32 s2, 0x80
	s_cbranch_scc1 .Ldt0_wlo0
	s_cmpk_eq_u32 s2, 0x80
	s_cbranch_scc1 .Ldt0_wlr0
	s_add_i32 s2, s2, -1

.Ldt0_ud0:
	v_mul_u32_u24_e32 v96, s7, v93
	s_lshl_b32 s6, s7, 6
	v_add_u32_e32 v96, v96, v94
	v_add_u32_e32 v97, s6, v96
	v_add_u32_e32 v98, s6, v97
	v_add_u32_e32 v99, s6, v98
	v_add_u32_e32 v100, s6, v99
	v_add_u32_e32 v101, s6, v100
	v_add_u32_e32 v102, s6, v101
	v_add_u32_e32 v103, s6, v102
	global_load_dwordx4 v[4:7], v96, s[64:65]
	global_load_dwordx4 v[8:11], v97, s[64:65]
	global_load_dwordx4 v[12:15], v98, s[64:65]
	global_load_dwordx4 v[16:19], v99, s[64:65]
	global_load_dwordx4 v[20:23], v100, s[64:65]
	global_load_dwordx4 v[24:27], v101, s[64:65]
	global_load_dwordx4 v[28:31], v102, s[64:65]
	global_load_dwordx4 v[32:35], v103, s[64:65]
	s_mov_b32 s72, 1
	s_add_u32 s52, s52, s84
	s_cmp_ge_u32 s52, s9
	s_cbranch_scc1 .Ldt0_procA
	s_cmpk_ge_u32 s52, 0x1410
	s_cbranch_scc1 .Ldt0_out1
	s_sub_i32 s0, s52, 0xa08
	s_mul_i32 s1, s0, 0xcc3
	s_lshr_b32 s1, s1, 20
	s_mul_i32 s2, s1, 0x141
	s_sub_u32 s2, s0, s2
	s_lshl_b32 s3, s2, 7
	s_mul_i32 s4, s1, 0x1410000
	s_add_u32 s3, s3, s4
	s_add_u32 s68, s54, s3
	s_addc_u32 s69, s55, 0
	s_mov_b32 s7, 0xa080
	s_lshl_b32 s4, s1, 10
	s_cmpk_lt_u32 s2, 0x80
	s_cbranch_scc1 .Ldt0_wlo1
	s_cmpk_eq_u32 s2, 0x80
	s_cbranch_scc1 .Ldt0_wlr1
	s_add_i32 s2, s2, -1

.Ldt0_wdA:
	v_cvt_pk_bf16_f32 v4, v4, v5
	v_cvt_pk_bf16_f32 v6, v6, v7
	v_cvt_pk_bf16_f32 v8, v8, v9
	v_cvt_pk_bf16_f32 v10, v10, v11
	v_cvt_pk_bf16_f32 v12, v12, v13
	v_cvt_pk_bf16_f32 v14, v14, v15
	v_cvt_pk_bf16_f32 v16, v16, v17
	v_cvt_pk_bf16_f32 v18, v18, v19
	v_cvt_pk_bf16_f32 v20, v20, v21
	v_cvt_pk_bf16_f32 v22, v22, v23
	v_cvt_pk_bf16_f32 v24, v24, v25
	v_cvt_pk_bf16_f32 v26, v26, v27
	v_cvt_pk_bf16_f32 v28, v28, v29
	v_cvt_pk_bf16_f32 v30, v30, v31
	v_cvt_pk_bf16_f32 v32, v32, v33
	v_cvt_pk_bf16_f32 v34, v34, v35
	v_cndmask_b32_e64 v5, v6, v4, s[74:75]
	v_cndmask_b32_e64 v7, v4, v6, s[74:75]
	v_cndmask_b32_e64 v9, v10, v8, s[74:75]
	v_cndmask_b32_e64 v11, v8, v10, s[74:75]
	v_cndmask_b32_e64 v13, v14, v12, s[74:75]
	v_cndmask_b32_e64 v15, v12, v14, s[74:75]
	v_cndmask_b32_e64 v17, v18, v16, s[74:75]
	v_cndmask_b32_e64 v19, v16, v18, s[74:75]
	v_cndmask_b32_e64 v21, v22, v20, s[74:75]
	v_cndmask_b32_e64 v23, v20, v22, s[74:75]
	v_cndmask_b32_e64 v25, v26, v24, s[74:75]
	v_cndmask_b32_e64 v27, v24, v26, s[74:75]
	v_cndmask_b32_e64 v29, v30, v28, s[74:75]
	v_cndmask_b32_e64 v31, v28, v30, s[74:75]
	v_cndmask_b32_e64 v33, v34, v32, s[74:75]
	v_cndmask_b32_e64 v35, v32, v34, s[74:75]
	v_mov_b32_dpp v4, v5 row_ror:8 row_mask:0xf bank_mask:0xf
	v_mov_b32_dpp v8, v9 row_ror:8 row_mask:0xf bank_mask:0xf
	v_mov_b32_dpp v12, v13 row_ror:8 row_mask:0xf bank_mask:0xf
	v_mov_b32_dpp v16, v17 row_ror:8 row_mask:0xf bank_mask:0xf
	v_mov_b32_dpp v20, v21 row_ror:8 row_mask:0xf bank_mask:0xf
	v_mov_b32_dpp v24, v25 row_ror:8 row_mask:0xf bank_mask:0xf
	v_mov_b32_dpp v28, v29 row_ror:8 row_mask:0xf bank_mask:0xf
	v_mov_b32_dpp v32, v33 row_ror:8 row_mask:0xf bank_mask:0xf
	s_nop 1
	v_perm_b32 v68, v7, v4, v104
	v_perm_b32 v69, v7, v4, v105
	v_perm_b32 v70, v11, v8, v104
	v_perm_b32 v71, v11, v8, v105
	v_perm_b32 v72, v15, v12, v104
	v_perm_b32 v73, v15, v12, v105
	v_perm_b32 v74, v19, v16, v104
	v_perm_b32 v75, v19, v16, v105
	v_perm_b32 v76, v23, v20, v104
	v_perm_b32 v77, v23, v20, v105
	v_perm_b32 v78, v27, v24, v104
	v_perm_b32 v79, v27, v24, v105
	v_perm_b32 v80, v31, v28, v104
	v_perm_b32 v81, v31, v28, v105
	v_perm_b32 v82, v35, v32, v104
	v_perm_b32 v83, v35, v32, v105
	s_mov_b64 s[70:71], s[66:67]
	s_mov_b32 s72, 0
	s_cmp_ge_u32 s52, s9
	s_cbranch_scc1 .Ldt0_nlA
	s_cmpk_ge_u32 s52, 0x1410
	s_cbranch_scc1 .Ldt0_out2
	s_sub_i32 s0, s52, 0xa08
	s_mul_i32 s1, s0, 0xcc3
	s_lshr_b32 s1, s1, 20
	s_mul_i32 s2, s1, 0x141
	s_sub_u32 s2, s0, s2
	s_lshl_b32 s3, s2, 7
	s_mul_i32 s4, s1, 0x1410000
	s_add_u32 s3, s3, s4
	s_add_u32 s64, s54, s3
	s_addc_u32 s65, s55, 0
	s_mov_b32 s7, 0xa080
	s_lshl_b32 s4, s1, 10
	s_cmpk_lt_u32 s2, 0x80
	s_cbranch_scc1 .Ldt0_wlo2
	s_cmpk_eq_u32 s2, 0x80
	s_cbranch_scc1 .Ldt0_wlr2
	s_add_i32 s2, s2, -1

.Ldt0_wdB:
	v_cvt_pk_bf16_f32 v36, v36, v37
	v_cvt_pk_bf16_f32 v38, v38, v39
	v_cvt_pk_bf16_f32 v40, v40, v41
	v_cvt_pk_bf16_f32 v42, v42, v43
	v_cvt_pk_bf16_f32 v44, v44, v45
	v_cvt_pk_bf16_f32 v46, v46, v47
	v_cvt_pk_bf16_f32 v48, v48, v49
	v_cvt_pk_bf16_f32 v50, v50, v51
	v_cvt_pk_bf16_f32 v52, v52, v53
	v_cvt_pk_bf16_f32 v54, v54, v55
	v_cvt_pk_bf16_f32 v56, v56, v57
	v_cvt_pk_bf16_f32 v58, v58, v59
	v_cvt_pk_bf16_f32 v60, v60, v61
	v_cvt_pk_bf16_f32 v62, v62, v63
	v_cvt_pk_bf16_f32 v64, v64, v65
	v_cvt_pk_bf16_f32 v66, v66, v67
	v_cndmask_b32_e64 v37, v38, v36, s[74:75]
	v_cndmask_b32_e64 v39, v36, v38, s[74:75]
	v_cndmask_b32_e64 v41, v42, v40, s[74:75]
	v_cndmask_b32_e64 v43, v40, v42, s[74:75]
	v_cndmask_b32_e64 v45, v46, v44, s[74:75]
	v_cndmask_b32_e64 v47, v44, v46, s[74:75]
	v_cndmask_b32_e64 v49, v50, v48, s[74:75]
	v_cndmask_b32_e64 v51, v48, v50, s[74:75]
	v_cndmask_b32_e64 v53, v54, v52, s[74:75]
	v_cndmask_b32_e64 v55, v52, v54, s[74:75]
	v_cndmask_b32_e64 v57, v58, v56, s[74:75]
	v_cndmask_b32_e64 v59, v56, v58, s[74:75]
	v_cndmask_b32_e64 v61, v62, v60, s[74:75]
	v_cndmask_b32_e64 v63, v60, v62, s[74:75]
	v_cndmask_b32_e64 v65, v66, v64, s[74:75]
	v_cndmask_b32_e64 v67, v64, v66, s[74:75]
	v_mov_b32_dpp v36, v37 row_ror:8 row_mask:0xf bank_mask:0xf
	v_mov_b32_dpp v40, v41 row_ror:8 row_mask:0xf bank_mask:0xf
	v_mov_b32_dpp v44, v45 row_ror:8 row_mask:0xf bank_mask:0xf
	v_mov_b32_dpp v48, v49 row_ror:8 row_mask:0xf bank_mask:0xf
	v_mov_b32_dpp v52, v53 row_ror:8 row_mask:0xf bank_mask:0xf
	v_mov_b32_dpp v56, v57 row_ror:8 row_mask:0xf bank_mask:0xf
	v_mov_b32_dpp v60, v61 row_ror:8 row_mask:0xf bank_mask:0xf
	v_mov_b32_dpp v64, v65 row_ror:8 row_mask:0xf bank_mask:0xf
	s_nop 1
	v_perm_b32 v68, v39, v36, v104
	v_perm_b32 v69, v39, v36, v105
	v_perm_b32 v70, v43, v40, v104
	v_perm_b32 v71, v43, v40, v105
	v_perm_b32 v72, v47, v44, v104
	v_perm_b32 v73, v47, v44, v105
	v_perm_b32 v74, v51, v48, v104
	v_perm_b32 v75, v51, v48, v105
	v_perm_b32 v76, v55, v52, v104
	v_perm_b32 v77, v55, v52, v105
	v_perm_b32 v78, v59, v56, v104
	v_perm_b32 v79, v59, v56, v105
	v_perm_b32 v80, v63, v60, v104
	v_perm_b32 v81, v63, v60, v105
	v_perm_b32 v82, v67, v64, v104
	v_perm_b32 v83, v67, v64, v105
	s_mov_b64 s[70:71], s[10:11]
	s_mov_b32 s73, 0
	s_cmp_ge_u32 s52, s9
	s_cbranch_scc1 .Ldt0_nlB
	s_cmpk_ge_u32 s52, 0x1410
	s_cbranch_scc1 .Ldt0_out3
	s_sub_i32 s0, s52, 0xa08
	s_mul_i32 s1, s0, 0xcc3
	s_lshr_b32 s1, s1, 20
	s_mul_i32 s2, s1, 0x141
	s_sub_u32 s2, s0, s2
	s_lshl_b32 s3, s2, 7
	s_mul_i32 s4, s1, 0x1410000
	s_add_u32 s3, s3, s4
	s_add_u32 s68, s54, s3
	s_addc_u32 s69, s55, 0
	s_mov_b32 s7, 0xa080
	s_lshl_b32 s4, s1, 10
	s_cmpk_lt_u32 s2, 0x80
	s_cbranch_scc1 .Ldt0_wlo3
	s_cmpk_eq_u32 s2, 0x80
	s_cbranch_scc1 .Ldt0_wlr3
	s_add_i32 s2, s2, -1

.LBB0_644:
	s_bfe_u32 s1, s54, 0x20003
	s_cmp_lg_u32 s60, s1
	s_cbranch_scc1 .Ldt1_skip
	s_mov_b32 s24, s54
	s_cmpk_lg_u32 s64, 0x100
	s_cbranch_scc1 .Ldt1_nrot
	s_xor_b32 s24, s24, 0x80
.Ldt1_nrot:
	s_addk_i32 s24, 0xa08
	s_mul_i32 s16, s64, 9
	s_add_u32 s24, s24, s16
	s_movk_i32 s16, 0x1c10
	s_cmp_ge_u32 s24, s16
	s_cbranch_scc1 .Ldt1_skip
	s_waitcnt lgkmcnt(0)
	s_barrier
	v_readlane_b32 s68, v254, 54
	v_readlane_b32 s69, v254, 55
	v_readlane_b32 s70, v253, 2
	v_readlane_b32 s71, v253, 3
	v_readlane_b32 s72, v253, 8
	v_readlane_b32 s73, v253, 9
	v_readlane_b32 s74, v253, 10
	v_readlane_b32 s75, v253, 11
	v_readlane_b32 s76, v254, 12
	v_readlane_b32 s77, v254, 13
	v_and_b32_e32 v106, 7, v180
	v_lshrrev_b32_e32 v93, 3, v180
	s_add_u32 s68, s68, 0xa080000
	s_addc_u32 s69, s69, 0
	s_add_u32 s72, s72, 0x5000000
	s_addc_u32 s73, s73, 0
	s_add_u32 s74, s74, 0x40000
	s_addc_u32 s75, s75, 0
	v_lshlrev_b32_e32 v94, 4, v106
	v_bfe_u32 v107, v180, 3, 1
	v_lshlrev_b32_e32 v108, 2, v106
	v_lshl_add_u32 v108, v107, 1, v108
	v_mul_u32_u24_e32 v84, 0x410, v108
	v_lshrrev_b32_e32 v109, 3, v93
	v_xor_b32_e32 v109, v109, v106
	v_lshlrev_b32_e32 v109, 3, v109
	v_and_b32_e32 v110, 6, v93
	v_or_b32_e32 v109, v109, v110
	v_lshl_add_u32 v84, v109, 1, v84
	v_cmp_ne_u32_e64 s[94:95], 0, v107
	v_mov_b32_e32 v104, 0x1000504
	v_mov_b32_e32 v105, 0x3020706
	v_mov_b32_e32 v111, 0x5040100
	v_mov_b32_e32 v112, 0x7060302
	v_cndmask_b32_e64 v104, v104, v111, s[94:95]
	v_cndmask_b32_e64 v105, v105, v112, s[94:95]
	v_lshrrev_b32_e32 v106, 6, v180
	v_and_b32_e32 v107, 63, v180
	v_lshrrev_b32_e32 v108, 2, v106
	v_add_u32_e32 v109, 0, v108
	v_xor_b32_e32 v109, v109, v107
	v_lshlrev_b32_e32 v109, 4, v109
	v_add_u32_e32 v110, 0, v106
	v_mul_u32_u24_e32 v110, 0x410, v110
	v_add_u32_e32 v85, v109, v110
	v_add_u32_e32 v109, 2, v108
	v_xor_b32_e32 v109, v109, v107
	v_lshlrev_b32_e32 v109, 4, v109
	v_add_u32_e32 v110, 8, v106
	v_mul_u32_u24_e32 v110, 0x410, v110
	v_add_u32_e32 v86, v109, v110
	v_add_u32_e32 v109, 4, v108
	v_xor_b32_e32 v109, v109, v107
	v_lshlrev_b32_e32 v109, 4, v109
	v_add_u32_e32 v110, 16, v106
	v_mul_u32_u24_e32 v110, 0x410, v110
	v_add_u32_e32 v87, v109, v110
	v_add_u32_e32 v109, 6, v108
	v_xor_b32_e32 v109, v109, v107
	v_lshlrev_b32_e32 v109, 4, v109
	v_add_u32_e32 v110, 24, v106
	v_mul_u32_u24_e32 v110, 0x410, v110
	v_add_u32_e32 v88, v109, v110
	v_lshlrev_b32_e32 v109, 13, v106
	v_lshl_add_u32 v89, v107, 4, v109
	v_add_u32_e32 v90, 0x10000, v89
	v_add_u32_e32 v91, 0x20000, v89
	v_add_u32_e32 v92, 0x30000, v89
	s_mov_b32 s25, 0
	s_mov_b32 s34, 0
	s_cmpk_ge_u32 s24, 0x1410
	s_cbranch_scc1 .Ldt1_out0
	s_sub_i32 s0, s24, 0xa08
	s_mul_i32 s1, s0, 0xcc3
	s_lshr_b32 s1, s1, 20
	s_mul_i32 s2, s1, 0x141
	s_sub_u32 s2, s0, s2
	s_lshl_b32 s3, s2, 7
	s_mul_i32 s12, s1, 0x1410000
	s_add_u32 s3, s3, s12
	s_add_u32 s78, s68, s3
	s_addc_u32 s79, s69, 0
	s_mov_b32 s15, 0xa080
	s_lshl_b32 s12, s1, 10
	s_cmpk_lt_u32 s2, 0x80
	s_cbranch_scc1 .Ldt1_wlo0
	s_cmpk_eq_u32 s2, 0x80
	s_cbranch_scc1 .Ldt1_wlr0
	s_add_i32 s2, s2, -1
.Ldt1_wlo0:
	s_lshl_b32 s13, s2, 18
	s_add_u32 s13, s13, s12
	s_add_u32 s80, s72, s13
	s_addc_u32 s81, s73, 0
	s_branch .Ldt1_ud0
.Ldt1_wlr0:
	s_add_u32 s80, s74, s12
	s_addc_u32 s81, s75, 0
	s_branch .Ldt1_ud0
.Ldt1_out0:
	s_sub_i32 s0, s24, 0x1410
	s_lshr_b32 s1, s0, 10
	s_bfe_u32 s2, s0, 0x30007
	s_and_b32 s3, s0, 0x7f
	s_lshl_b32 s12, s1, 26
	s_lshl_b32 s13, s3, 7
	s_add_u32 s12, s12, s13
	s_lshl_b32 s13, s2, 23
	s_add_u32 s12, s12, s13
	s_add_u32 s78, s70, s12
	s_addc_u32 s79, s71, 0
	s_lshl_b32 s12, s1, 25
	s_lshl_b32 s13, s3, 18
	s_add_u32 s12, s12, s13
	s_lshl_b32 s13, s2, 10
	s_add_u32 s12, s12, s13
	s_add_u32 s80, s76, s12
	s_addc_u32 s81, s77, 0
	s_movk_i32 s15, 0x4000
.Ldt1_ud0:
	v_mul_u32_u24_e32 v96, s15, v93
	s_lshl_b32 s14, s15, 6
	v_add_u32_e32 v96, v96, v94
	v_add_u32_e32 v97, s14, v96
	v_add_u32_e32 v98, s14, v97
	v_add_u32_e32 v99, s14, v98
	v_add_u32_e32 v100, s14, v99
	v_add_u32_e32 v101, s14, v100
	v_add_u32_e32 v102, s14, v101
	v_add_u32_e32 v103, s14, v102
	global_load_dwordx4 v[4:7], v96, s[78:79]
	global_load_dwordx4 v[8:11], v97, s[78:79]
	global_load_dwordx4 v[12:15], v98, s[78:79]
	global_load_dwordx4 v[16:19], v99, s[78:79]
	global_load_dwordx4 v[20:23], v100, s[78:79]
	global_load_dwordx4 v[24:27], v101, s[78:79]
	global_load_dwordx4 v[28:31], v102, s[78:79]
	global_load_dwordx4 v[32:35], v103, s[78:79]
	s_mov_b32 s32, 1
	s_add_u32 s24, s24, s64
	s_cmp_ge_u32 s24, s16
	s_cbranch_scc1 .Ldt1_procA
	s_cmpk_ge_u32 s24, 0x1410
	s_cbranch_scc1 .Ldt1_out1
	s_sub_i32 s0, s24, 0xa08
	s_mul_i32 s1, s0, 0xcc3
	s_lshr_b32 s1, s1, 20
	s_mul_i32 s2, s1, 0x141
	s_sub_u32 s2, s0, s2
	s_lshl_b32 s3, s2, 7
	s_mul_i32 s12, s1, 0x1410000
	s_add_u32 s3, s3, s12
	s_add_u32 s82, s68, s3
	s_addc_u32 s83, s69, 0
	s_mov_b32 s15, 0xa080
	s_lshl_b32 s12, s1, 10
	s_cmpk_lt_u32 s2, 0x80
	s_cbranch_scc1 .Ldt1_wlo1
	s_cmpk_eq_u32 s2, 0x80
	s_cbranch_scc1 .Ldt1_wlr1
	s_add_i32 s2, s2, -1
.Ldt1_wlo1:
	s_lshl_b32 s13, s2, 18
	s_add_u32 s13, s13, s12
	s_add_u32 s20, s72, s13
	s_addc_u32 s21, s73, 0
	s_branch .Ldt1_ud1
.Ldt1_wlr1:
	s_add_u32 s20, s74, s12
	s_addc_u32 s21, s75, 0
	s_branch .Ldt1_ud1
.Ldt1_out1:
	s_sub_i32 s0, s24, 0x1410
	s_lshr_b32 s1, s0, 10
	s_bfe_u32 s2, s0, 0x30007
	s_and_b32 s3, s0, 0x7f
	s_lshl_b32 s12, s1, 26
	s_lshl_b32 s13, s3, 7
	s_add_u32 s12, s12, s13
	s_lshl_b32 s13, s2, 23
	s_add_u32 s12, s12, s13
	s_add_u32 s82, s70, s12
	s_addc_u32 s83, s71, 0
	s_lshl_b32 s12, s1, 25
	s_lshl_b32 s13, s3, 18
	s_add_u32 s12, s12, s13
	s_lshl_b32 s13, s2, 10
	s_add_u32 s12, s12, s13
	s_add_u32 s20, s76, s12
	s_addc_u32 s21, s77, 0
	s_movk_i32 s15, 0x4000
.Ldt1_ud1:
	v_mul_u32_u24_e32 v96, s15, v93
	s_lshl_b32 s14, s15, 6
	v_add_u32_e32 v96, v96, v94
	v_add_u32_e32 v97, s14, v96
	v_add_u32_e32 v98, s14, v97
	v_add_u32_e32 v99, s14, v98
	v_add_u32_e32 v100, s14, v99
	v_add_u32_e32 v101, s14, v100
	v_add_u32_e32 v102, s14, v101
	v_add_u32_e32 v103, s14, v102
	global_load_dwordx4 v[36:39], v96, s[82:83]
	global_load_dwordx4 v[40:43], v97, s[82:83]
	global_load_dwordx4 v[44:47], v98, s[82:83]
	global_load_dwordx4 v[48:51], v99, s[82:83]
	global_load_dwordx4 v[52:55], v100, s[82:83]
	global_load_dwordx4 v[56:59], v101, s[82:83]
	global_load_dwordx4 v[60:63], v102, s[82:83]
	global_load_dwordx4 v[64:67], v103, s[82:83]
	s_mov_b32 s34, 1
	s_add_u32 s24, s24, s64
.Ldt1_procA:
	s_cmp_eq_u32 s34, 0
	s_cbranch_scc1 .Ldt1_w0A
	s_cmp_lt_u32 s25, 2
	s_cbranch_scc1 .Ldt1_wsA
	s_waitcnt vmcnt(16)
	s_branch .Ldt1_wdA
.Ldt1_wsA:
	s_cmp_eq_u32 s25, 0
	s_cbranch_scc1 .Ldt1_w8A
	s_waitcnt vmcnt(12)
	s_branch .Ldt1_wdA

.Ldt1_wdA:
	v_cvt_pk_bf16_f32 v4, v4, v5
	v_cvt_pk_bf16_f32 v6, v6, v7
	v_cvt_pk_bf16_f32 v8, v8, v9
	v_cvt_pk_bf16_f32 v10, v10, v11
	v_cvt_pk_bf16_f32 v12, v12, v13
	v_cvt_pk_bf16_f32 v14, v14, v15
	v_cvt_pk_bf16_f32 v16, v16, v17
	v_cvt_pk_bf16_f32 v18, v18, v19
	v_cvt_pk_bf16_f32 v20, v20, v21
	v_cvt_pk_bf16_f32 v22, v22, v23
	v_cvt_pk_bf16_f32 v24, v24, v25
	v_cvt_pk_bf16_f32 v26, v26, v27
	v_cvt_pk_bf16_f32 v28, v28, v29
	v_cvt_pk_bf16_f32 v30, v30, v31
	v_cvt_pk_bf16_f32 v32, v32, v33
	v_cvt_pk_bf16_f32 v34, v34, v35
	v_cndmask_b32_e64 v5, v6, v4, s[94:95]
	v_cndmask_b32_e64 v7, v4, v6, s[94:95]
	v_cndmask_b32_e64 v9, v10, v8, s[94:95]
	v_cndmask_b32_e64 v11, v8, v10, s[94:95]
	v_cndmask_b32_e64 v13, v14, v12, s[94:95]
	v_cndmask_b32_e64 v15, v12, v14, s[94:95]
	v_cndmask_b32_e64 v17, v18, v16, s[94:95]
	v_cndmask_b32_e64 v19, v16, v18, s[94:95]
	v_cndmask_b32_e64 v21, v22, v20, s[94:95]
	v_cndmask_b32_e64 v23, v20, v22, s[94:95]
	v_cndmask_b32_e64 v25, v26, v24, s[94:95]
	v_cndmask_b32_e64 v27, v24, v26, s[94:95]
	v_cndmask_b32_e64 v29, v30, v28, s[94:95]
	v_cndmask_b32_e64 v31, v28, v30, s[94:95]
	v_cndmask_b32_e64 v33, v34, v32, s[94:95]
	v_cndmask_b32_e64 v35, v32, v34, s[94:95]
	v_mov_b32_dpp v4, v5 row_ror:8 row_mask:0xf bank_mask:0xf
	v_mov_b32_dpp v8, v9 row_ror:8 row_mask:0xf bank_mask:0xf
	v_mov_b32_dpp v12, v13 row_ror:8 row_mask:0xf bank_mask:0xf
	v_mov_b32_dpp v16, v17 row_ror:8 row_mask:0xf bank_mask:0xf
	v_mov_b32_dpp v20, v21 row_ror:8 row_mask:0xf bank_mask:0xf
	v_mov_b32_dpp v24, v25 row_ror:8 row_mask:0xf bank_mask:0xf
	v_mov_b32_dpp v28, v29 row_ror:8 row_mask:0xf bank_mask:0xf
	v_mov_b32_dpp v32, v33 row_ror:8 row_mask:0xf bank_mask:0xf
	s_nop 1
	v_perm_b32 v68, v7, v4, v104
	v_perm_b32 v69, v7, v4, v105
	v_perm_b32 v70, v11, v8, v104
	v_perm_b32 v71, v11, v8, v105
	v_perm_b32 v72, v15, v12, v104
	v_perm_b32 v73, v15, v12, v105
	v_perm_b32 v74, v19, v16, v104
	v_perm_b32 v75, v19, v16, v105
	v_perm_b32 v76, v23, v20, v104
	v_perm_b32 v77, v23, v20, v105
	v_perm_b32 v78, v27, v24, v104
	v_perm_b32 v79, v27, v24, v105
	v_perm_b32 v80, v31, v28, v104
	v_perm_b32 v81, v31, v28, v105
	v_perm_b32 v82, v35, v32, v104
	v_perm_b32 v83, v35, v32, v105
	s_mov_b64 s[90:91], s[80:81]
	s_mov_b32 s32, 0
	s_cmp_ge_u32 s24, s16
	s_cbranch_scc1 .Ldt1_nlA
	s_cmpk_ge_u32 s24, 0x1410
	s_cbranch_scc1 .Ldt1_out2
	s_sub_i32 s0, s24, 0xa08
	s_mul_i32 s1, s0, 0xcc3
	s_lshr_b32 s1, s1, 20
	s_mul_i32 s2, s1, 0x141
	s_sub_u32 s2, s0, s2
	s_lshl_b32 s3, s2, 7
	s_mul_i32 s12, s1, 0x1410000
	s_add_u32 s3, s3, s12
	s_add_u32 s78, s68, s3
	s_addc_u32 s79, s69, 0
	s_mov_b32 s15, 0xa080
	s_lshl_b32 s12, s1, 10
	s_cmpk_lt_u32 s2, 0x80
	s_cbranch_scc1 .Ldt1_wlo2
	s_cmpk_eq_u32 s2, 0x80
	s_cbranch_scc1 .Ldt1_wlr2
	s_add_i32 s2, s2, -1

.Ldt1_ud2:
	v_mul_u32_u24_e32 v96, s15, v93
	s_lshl_b32 s14, s15, 6
	v_add_u32_e32 v96, v96, v94
	v_add_u32_e32 v97, s14, v96
	v_add_u32_e32 v98, s14, v97
	v_add_u32_e32 v99, s14, v98
	v_add_u32_e32 v100, s14, v99
	v_add_u32_e32 v101, s14, v100
	v_add_u32_e32 v102, s14, v101
	v_add_u32_e32 v103, s14, v102
	global_load_dwordx4 v[4:7], v96, s[78:79]
	global_load_dwordx4 v[8:11], v97, s[78:79]
	global_load_dwordx4 v[12:15], v98, s[78:79]
	global_load_dwordx4 v[16:19], v99, s[78:79]
	global_load_dwordx4 v[20:23], v100, s[78:79]
	global_load_dwordx4 v[24:27], v101, s[78:79]
	global_load_dwordx4 v[28:31], v102, s[78:79]
	global_load_dwordx4 v[32:35], v103, s[78:79]
	s_mov_b32 s32, 1
	s_add_u32 s24, s24, s64
.Ldt1_nlA:
	ds_write_b32 v84, v68 offset:0
	ds_write_b32 v84, v69 offset:1040
	ds_write_b32 v84, v70 offset:128
	ds_write_b32 v84, v71 offset:1168
	ds_write_b32 v84, v72 offset:256
	ds_write_b32 v84, v73 offset:1296
	ds_write_b32 v84, v74 offset:384
	ds_write_b32 v84, v75 offset:1424
	ds_write_b32 v84, v76 offset:512
	ds_write_b32 v84, v77 offset:1552
	ds_write_b32 v84, v78 offset:640
	ds_write_b32 v84, v79 offset:1680
	ds_write_b32 v84, v80 offset:768
	ds_write_b32 v84, v81 offset:1808
	ds_write_b32 v84, v82 offset:896
	ds_write_b32 v84, v83 offset:1936
	s_waitcnt lgkmcnt(0)
	s_barrier
	ds_read_b128 v[68:71], v85 offset:0
	ds_read_b128 v[72:75], v86 offset:0
	ds_read_b128 v[76:79], v87 offset:0
	ds_read_b128 v[80:83], v88 offset:0
	s_waitcnt lgkmcnt(3)
	global_store_dwordx4 v89, v[68:71], s[90:91]
	s_waitcnt lgkmcnt(2)
	global_store_dwordx4 v90, v[72:75], s[90:91]
	s_waitcnt lgkmcnt(1)
	global_store_dwordx4 v91, v[76:79], s[90:91]
	s_waitcnt lgkmcnt(0)
	global_store_dwordx4 v92, v[80:83], s[90:91]
	s_add_u32 s25, s25, 1
	s_cmp_eq_u32 s34, 0
	s_cbranch_scc1 .Ldt1_end
.Ldt1_procB:
	s_cmp_eq_u32 s32, 0
	s_cbranch_scc1 .Ldt1_w0B
	s_cmp_lt_u32 s25, 2
	s_cbranch_scc1 .Ldt1_wsB
	s_waitcnt vmcnt(16)
	s_branch .Ldt1_wdB

.Ldt1_wdB:
	v_cvt_pk_bf16_f32 v36, v36, v37
	v_cvt_pk_bf16_f32 v38, v38, v39
	v_cvt_pk_bf16_f32 v40, v40, v41
	v_cvt_pk_bf16_f32 v42, v42, v43
	v_cvt_pk_bf16_f32 v44, v44, v45
	v_cvt_pk_bf16_f32 v46, v46, v47
	v_cvt_pk_bf16_f32 v48, v48, v49
	v_cvt_pk_bf16_f32 v50, v50, v51
	v_cvt_pk_bf16_f32 v52, v52, v53
	v_cvt_pk_bf16_f32 v54, v54, v55
	v_cvt_pk_bf16_f32 v56, v56, v57
	v_cvt_pk_bf16_f32 v58, v58, v59
	v_cvt_pk_bf16_f32 v60, v60, v61
	v_cvt_pk_bf16_f32 v62, v62, v63
	v_cvt_pk_bf16_f32 v64, v64, v65
	v_cvt_pk_bf16_f32 v66, v66, v67
	v_cndmask_b32_e64 v37, v38, v36, s[94:95]
	v_cndmask_b32_e64 v39, v36, v38, s[94:95]
	v_cndmask_b32_e64 v41, v42, v40, s[94:95]
	v_cndmask_b32_e64 v43, v40, v42, s[94:95]
	v_cndmask_b32_e64 v45, v46, v44, s[94:95]
	v_cndmask_b32_e64 v47, v44, v46, s[94:95]
	v_cndmask_b32_e64 v49, v50, v48, s[94:95]
	v_cndmask_b32_e64 v51, v48, v50, s[94:95]
	v_cndmask_b32_e64 v53, v54, v52, s[94:95]
	v_cndmask_b32_e64 v55, v52, v54, s[94:95]
	v_cndmask_b32_e64 v57, v58, v56, s[94:95]
	v_cndmask_b32_e64 v59, v56, v58, s[94:95]
	v_cndmask_b32_e64 v61, v62, v60, s[94:95]
	v_cndmask_b32_e64 v63, v60, v62, s[94:95]
	v_cndmask_b32_e64 v65, v66, v64, s[94:95]
	v_cndmask_b32_e64 v67, v64, v66, s[94:95]
	v_mov_b32_dpp v36, v37 row_ror:8 row_mask:0xf bank_mask:0xf
	v_mov_b32_dpp v40, v41 row_ror:8 row_mask:0xf bank_mask:0xf
	v_mov_b32_dpp v44, v45 row_ror:8 row_mask:0xf bank_mask:0xf
	v_mov_b32_dpp v48, v49 row_ror:8 row_mask:0xf bank_mask:0xf
	v_mov_b32_dpp v52, v53 row_ror:8 row_mask:0xf bank_mask:0xf
	v_mov_b32_dpp v56, v57 row_ror:8 row_mask:0xf bank_mask:0xf
	v_mov_b32_dpp v60, v61 row_ror:8 row_mask:0xf bank_mask:0xf
	v_mov_b32_dpp v64, v65 row_ror:8 row_mask:0xf bank_mask:0xf
	s_nop 1
	v_perm_b32 v68, v39, v36, v104
	v_perm_b32 v69, v39, v36, v105
	v_perm_b32 v70, v43, v40, v104
	v_perm_b32 v71, v43, v40, v105
	v_perm_b32 v72, v47, v44, v104
	v_perm_b32 v73, v47, v44, v105
	v_perm_b32 v74, v51, v48, v104
	v_perm_b32 v75, v51, v48, v105
	v_perm_b32 v76, v55, v52, v104
	v_perm_b32 v77, v55, v52, v105
	v_perm_b32 v78, v59, v56, v104
	v_perm_b32 v79, v59, v56, v105
	v_perm_b32 v80, v63, v60, v104
	v_perm_b32 v81, v63, v60, v105
	v_perm_b32 v82, v67, v64, v104
	v_perm_b32 v83, v67, v64, v105
	s_mov_b64 s[90:91], s[20:21]
	s_mov_b32 s34, 0
	s_cmp_ge_u32 s24, s16
	s_cbranch_scc1 .Ldt1_nlB
	s_cmpk_ge_u32 s24, 0x1410
	s_cbranch_scc1 .Ldt1_out3
	s_sub_i32 s0, s24, 0xa08
	s_mul_i32 s1, s0, 0xcc3
	s_lshr_b32 s1, s1, 20
	s_mul_i32 s2, s1, 0x141
	s_sub_u32 s2, s0, s2
	s_lshl_b32 s3, s2, 7
	s_mul_i32 s12, s1, 0x1410000
	s_add_u32 s3, s3, s12
	s_add_u32 s82, s68, s3
	s_addc_u32 s83, s69, 0
	s_mov_b32 s15, 0xa080
	s_lshl_b32 s12, s1, 10
	s_cmpk_lt_u32 s2, 0x80
	s_cbranch_scc1 .Ldt1_wlo3
	s_cmpk_eq_u32 s2, 0x80
	s_cbranch_scc1 .Ldt1_wlr3
	s_add_i32 s2, s2, -1

.Ldt1_nlB:
	ds_write_b32 v84, v68 offset:33280
	ds_write_b32 v84, v69 offset:34320
	ds_write_b32 v84, v70 offset:33408
	ds_write_b32 v84, v71 offset:34448
	ds_write_b32 v84, v72 offset:33536
	ds_write_b32 v84, v73 offset:34576
	ds_write_b32 v84, v74 offset:33664
	ds_write_b32 v84, v75 offset:34704
	ds_write_b32 v84, v76 offset:33792
	ds_write_b32 v84, v77 offset:34832
	ds_write_b32 v84, v78 offset:33920
	ds_write_b32 v84, v79 offset:34960
	ds_write_b32 v84, v80 offset:34048
	ds_write_b32 v84, v81 offset:35088
	ds_write_b32 v84, v82 offset:34176
	ds_write_b32 v84, v83 offset:35216
	s_waitcnt lgkmcnt(0)
	s_barrier
	ds_read_b128 v[68:71], v85 offset:33280
	ds_read_b128 v[72:75], v86 offset:33280
	ds_read_b128 v[76:79], v87 offset:33280
	ds_read_b128 v[80:83], v88 offset:33280
	s_waitcnt lgkmcnt(3)
	global_store_dwordx4 v89, v[68:71], s[90:91]
	s_waitcnt lgkmcnt(2)
	global_store_dwordx4 v90, v[72:75], s[90:91]
	s_waitcnt lgkmcnt(1)
	global_store_dwordx4 v91, v[76:79], s[90:91]
	s_waitcnt lgkmcnt(0)
	global_store_dwordx4 v92, v[80:83], s[90:91]
	s_add_u32 s25, s25, 1
	s_cmp_eq_u32 s32, 0
	s_cbranch_scc0 .Ldt1_procA
.Ldt1_end:
	s_nop 1
	s_waitcnt lgkmcnt(0)
	s_barrier
.Ldt1_skip:
	s_lshl_b32 s0, s60, 8
	s_add_i32 s12, s0, s54
	s_mul_i32 s0, s12, 0x8200
	v_mov_b32_e32 v171, v180
	s_mul_hi_i32 s1, s12, 0x8200
	s_add_u32 s0, s46, s0
	s_movk_i32 s2, 0x820
	s_addc_u32 s1, s47, s1
	v_lshlrev_b32_e32 v120, 2, v171
	v_lshlrev_b32_e32 v186, 4, v171
	v_ashrrev_i32_e32 v121, 31, v120
	global_load_dwordx4 v[188:191], v186, s[0:1]
	v_add_u32_e32 v172, 0x200, v171
	v_add_u32_e32 v187, 0x2000, v186
	v_lshlrev_b32_e32 v126, 2, v172
	global_load_dwordx4 v[192:195], v187, s[0:1]
	v_add_u32_e32 v173, 0x400, v171
	v_add_u32_e32 v187, 0x4000, v186
	v_lshlrev_b32_e32 v124, 2, v173
	global_load_dwordx4 v[196:199], v187, s[0:1]
	v_add_u32_e32 v174, 0x600, v171
	v_add_u32_e32 v187, 0x6000, v186
	v_lshlrev_b32_e32 v122, 2, v174
	global_load_dwordx4 v[200:203], v187, s[0:1]
	v_cmp_gt_i32_e32 vcc, 32, v171
	v_add_u32_e32 v187, 0x8000, v186
	s_nop 1
	v_cndmask_b32_e32 v187, 0, v187, vcc
	global_load_dwordx4 v[204:207], v187, s[0:1]
	s_ashr_i32 s61, s12, 3
	s_lshl_b32 s0, s61, 6
	s_cmp_lt_i32 s61, 64
	s_cselect_b64 s[20:21], -1, 0
	s_add_i32 s1, s0, 0xfffff000
	s_lshr_b32 s1, s1, 11
	s_ashr_i32 s2, s12, 5
	s_cmp_gt_i32 s61, 63
	v_readlane_b32 s68, v254, 12
	s_cselect_b64 s[24:25], -1, 0
	v_ashrrev_i32_e32 v170, 3, v171
	v_readlane_b32 s74, v254, 18
	v_readlane_b32 s75, v254, 19
	s_and_b64 vcc, s[24:25], exec
	v_add_u32_e32 v116, s0, v170
	v_mov_b64_e32 v[0:1], s[74:75]
	s_cselect_b32 s13, s1, s2
	v_and_b32_e32 v11, 7, v171
	v_mad_i64_i32 v[118:119], s[0:1], v116, s84, v[0:1]
	s_mov_b32 s7, s9
	v_lshl_add_u64 v[0:1], v[118:119], 0, s[6:7]
	v_lshlrev_b32_e32 v176, 4, v11
	v_lshl_add_u64 v[0:1], v[0:1], 0, v[176:177]
	v_add_co_u32_e64 v4, s[0:1], s92, v0
	s_nop 1
	v_addc_co_u32_e64 v5, s[0:1], 0, v1, s[0:1]
	global_load_dwordx4 v[208:211], v[4:5], off
	global_load_dwordx4 v[212:215], v[4:5], off offset:1024
	v_and_b32_e32 v232, 7, v171
	v_lshlrev_b32_e32 v232, 5, v232
	v_add_u32_e32 v232, s8, v232
	v_add_u32_e32 v232, 0x1800, v232
	v_mov_b32_e32 v233, 0
	v_lshl_add_u64 v[232:233], v[118:119], 0, v[232:233]
	global_load_dwordx4 v[224:227], v[232:233], off
	global_load_dwordx4 v[228:231], v[232:233], off offset:16
	s_waitcnt vmcnt(4)
	ds_write_b128 v186, v[188:191]
	ds_write_b128 v186, v[192:195] offset:8192
	ds_write_b128 v186, v[196:199] offset:16384
	ds_write_b128 v186, v[200:203] offset:24576
	v_cmp_gt_i32_e64 s[98:99], 32, v171
	s_and_saveexec_b64 s[62:63], s[98:99]
	ds_write_b128 v186, v[204:207] offset:32768
	s_mov_b64 exec, s[62:63]
	s_waitcnt lgkmcnt(0)
	s_barrier
	v_lshlrev_b32_e32 v8, 5, v11
	v_add_u32_e32 v10, 0, v8
	s_movk_i32 s0, 0x104
	v_mad_u64_u32 v[12:13], s[0:1], v170, s0, v[10:11]
	ds_read2_b32 v[14:15], v12 offset1:1
	v_add_u32_e32 v13, 0x607c, v10
	s_mov_b64 s[0:1], 0x1800
	v_mul_u32_u24_e32 v11, 0x900, v11
	s_lshl_b32 s14, s13, 2
	s_mov_b32 s15, s9
	s_mov_b32 s3, s9
	v_readlane_b32 s69, v254, 13
	v_readlane_b32 s70, v254, 14
	v_readlane_b32 s71, v254, 15
	v_readlane_b32 s72, v254, 16
	v_readlane_b32 s73, v254, 17
	v_readlane_b32 s76, v254, 20
	v_readlane_b32 s77, v254, 21
	v_readlane_b32 s78, v254, 22
	v_readlane_b32 s79, v254, 23
	v_readlane_b32 s80, v254, 24
	v_readlane_b32 s81, v254, 25
	v_readlane_b32 s82, v254, 26
	v_readlane_b32 s83, v254, 27
	s_waitcnt vmcnt(3)
	v_lshlrev_b32_e32 v6, 16, v208
	v_and_b32_e32 v20, 0xffff0000, v208
	v_lshlrev_b32_e32 v32, 16, v209
	v_and_b32_e32 v33, 0xffff0000, v209
	v_lshlrev_b32_e32 v40, 16, v210
	v_and_b32_e32 v41, 0xffff0000, v210
	v_lshlrev_b32_e32 v49, 16, v211
	v_and_b32_e32 v16, 0xffff0000, v211
	v_mul_f32_e32 v17, 0x3e000000, v6
	v_mul_f32_e32 v49, 0x3e000000, v49
	s_waitcnt vmcnt(2)
	v_lshlrev_b32_e32 v22, 16, v212
	v_and_b32_e32 v34, 0xffff0000, v212
	v_add_u32_e32 v0, 0x4100, v12
	v_lshlrev_b32_e32 v35, 16, v213
	v_and_b32_e32 v42, 0xffff0000, v213
	v_lshlrev_b32_e32 v37, 16, v214
	v_and_b32_e32 v50, 0xffff0000, v214
	v_lshlrev_b32_e32 v24, 16, v215
	v_and_b32_e32 v9, 0xffff0000, v215
	ds_read2_b32 v[28:29], v0 offset1:1
	ds_read_b128 v[4:7], v10 offset:8320
	ds_read_b128 v[0:3], v10 offset:8336
	ds_read2_b32 v[30:31], v13 offset1:1
	s_waitcnt lgkmcnt(4)
	v_mul_f32_e32 v13, 0x3fb8aa3b, v14
	v_exp_f32_e32 v13, v13
	s_nop 0
	v_mul_f32_e32 v23, v17, v13
	s_waitcnt lgkmcnt(3)
	v_mul_f32_e32 v13, 0x3fb8aa3b, v28
	v_exp_f32_e32 v13, v13
	s_nop 0
	v_mul_f32_e32 v21, v17, v13
	s_waitcnt lgkmcnt(2)
	v_sub_f32_e32 v13, v14, v4
	v_sub_f32_e32 v4, v4, v14
	v_mul_f32_e32 v4, 0x3fb8aa3b, v4
	v_exp_f32_e32 v4, v4
	v_mul_f32_e32 v13, 0x3fb8aa3b, v13
	v_exp_f32_e32 v13, v13
	v_mul_f32_e32 v14, 0x3fb8aa3b, v15
	v_mul_f32_e32 v18, v4, v22
	s_waitcnt lgkmcnt(0)
	v_sub_f32_e32 v4, v28, v30
	v_mul_f32_e32 v4, 0x3fb8aa3b, v4
	v_exp_f32_e32 v4, v4
	v_mul_f32_e32 v19, v17, v13
	v_exp_f32_e32 v14, v14
	v_mul_f32_e32 v17, v17, v4
	v_sub_f32_e32 v4, v30, v28
	v_mul_f32_e32 v4, 0x3fb8aa3b, v4
	v_exp_f32_e32 v4, v4
	s_nop 0
	v_mul_f32_e32 v13, v4, v22
	v_mul_f32_e32 v4, 0x3e000000, v20
	v_mul_f32_e32 v28, v4, v14
	v_mul_f32_e32 v14, 0x3fb8aa3b, v29
	v_exp_f32_e32 v14, v14
	s_nop 0
	v_mul_f32_e32 v27, v4, v14
	v_sub_f32_e32 v14, v15, v5
	v_sub_f32_e32 v5, v5, v15
	v_mul_f32_e32 v5, 0x3fb8aa3b, v5
	v_exp_f32_e32 v5, v5
	v_mul_f32_e32 v14, 0x3fb8aa3b, v14
	v_exp_f32_e32 v14, v14
	v_mul_f32_e32 v25, v5, v34
	v_sub_f32_e32 v5, v29, v31
	v_mul_f32_e32 v5, 0x3fb8aa3b, v5
	v_exp_f32_e32 v5, v5
	v_mul_f32_e32 v26, v4, v14
	ds_read2_b32 v[14:15], v12 offset0:2 offset1:3
	v_mul_f32_e32 v22, v4, v5
	v_sub_f32_e32 v4, v31, v29
	v_mul_f32_e32 v4, 0x3fb8aa3b, v4
	v_exp_f32_e32 v4, v4
	v_add_u32_e32 v29, 0x6084, v10
	ds_read2_b32 v[38:39], v29 offset1:1
	v_mul_f32_e32 v20, v4, v34
	v_add_u32_e32 v4, 0x4108, v12
	ds_read2_b32 v[4:5], v4 offset1:1
	s_waitcnt lgkmcnt(2)
	v_mul_f32_e32 v29, 0x3fb8aa3b, v14
	v_exp_f32_e32 v29, v29
	v_mul_f32_e32 v34, 0x3e000000, v32
	v_mul_f32_e32 v32, v34, v29
	s_waitcnt lgkmcnt(0)
	v_mul_f32_e32 v29, 0x3fb8aa3b, v4
	v_exp_f32_e32 v29, v29
	s_nop 0
	v_mul_f32_e32 v31, v34, v29
	v_sub_f32_e32 v29, v14, v6
	v_sub_f32_e32 v6, v6, v14
	v_mul_f32_e32 v29, 0x3fb8aa3b, v29
	v_mul_f32_e32 v6, 0x3fb8aa3b, v6
	v_exp_f32_e32 v29, v29
	v_exp_f32_e32 v6, v6
	v_mul_f32_e32 v30, v34, v29
	v_mul_f32_e32 v29, v6, v35
	v_sub_f32_e32 v6, v4, v38
	v_sub_f32_e32 v4, v38, v4
	v_mul_f32_e32 v6, 0x3fb8aa3b, v6
	v_mul_f32_e32 v4, 0x3fb8aa3b, v4
	v_exp_f32_e32 v6, v6
	v_exp_f32_e32 v4, v4
	v_mul_f32_e32 v38, 0x3e000000, v40
	v_mul_f32_e32 v14, v34, v6
	v_mul_f32_e32 v6, v4, v35
	v_mul_f32_e32 v4, 0x3e000000, v33
	v_mul_f32_e32 v33, 0x3fb8aa3b, v15
	v_exp_f32_e32 v33, v33
	s_nop 0
	v_mul_f32_e32 v36, v4, v33
	v_mul_f32_e32 v33, 0x3fb8aa3b, v5
	v_exp_f32_e32 v33, v33
	s_nop 0
	v_mul_f32_e32 v35, v4, v33
	v_sub_f32_e32 v33, v15, v7
	v_sub_f32_e32 v7, v7, v15
	v_mul_f32_e32 v33, 0x3fb8aa3b, v33
	v_mul_f32_e32 v7, 0x3fb8aa3b, v7
	v_exp_f32_e32 v33, v33
	v_exp_f32_e32 v7, v7
	v_mul_f32_e32 v34, v4, v33
	v_mul_f32_e32 v33, v7, v42
	v_sub_f32_e32 v7, v5, v39
	v_mul_f32_e32 v7, 0x3fb8aa3b, v7
	v_exp_f32_e32 v7, v7
	s_nop 0
	v_mul_f32_e32 v15, v4, v7
	v_sub_f32_e32 v4, v39, v5
	v_mul_f32_e32 v4, 0x3fb8aa3b, v4
	v_exp_f32_e32 v4, v4
	v_add_u32_e32 v39, 0x4110, v12
	ds_read2_b32 v[52:53], v39 offset1:1
	v_add_u32_e32 v39, 0x608c, v10
	v_mul_f32_e32 v7, v4, v42
	ds_read2_b32 v[4:5], v12 offset0:4 offset1:5
	ds_read2_b32 v[54:55], v39 offset1:1
	v_add_u32_e32 v10, 0x6094, v10
	s_waitcnt lgkmcnt(1)
	v_mul_f32_e32 v39, 0x3fb8aa3b, v4
	v_exp_f32_e32 v39, v39
	s_nop 0
	v_mul_f32_e32 v44, v38, v39
	v_mul_f32_e32 v39, 0x3fb8aa3b, v52
	v_exp_f32_e32 v39, v39
	s_nop 0
	v_mul_f32_e32 v42, v38, v39
	v_sub_f32_e32 v39, v4, v0
	v_sub_f32_e32 v0, v0, v4
	v_mul_f32_e32 v39, 0x3fb8aa3b, v39
	v_mul_f32_e32 v0, 0x3fb8aa3b, v0
	v_exp_f32_e32 v39, v39
	v_exp_f32_e32 v0, v0
	v_mul_f32_e32 v4, 0x3fb8aa3b, v5
	v_exp_f32_e32 v4, v4
	v_mul_f32_e32 v40, v38, v39
	v_mul_f32_e32 v39, v0, v37
	s_waitcnt lgkmcnt(0)
	v_sub_f32_e32 v0, v52, v54
	v_mul_f32_e32 v0, 0x3fb8aa3b, v0
	v_exp_f32_e32 v0, v0
	s_nop 0
	v_mul_f32_e32 v38, v38, v0
	v_sub_f32_e32 v0, v54, v52
	v_mul_f32_e32 v0, 0x3fb8aa3b, v0
	v_exp_f32_e32 v0, v0
	s_nop 0
	v_mul_f32_e32 v37, v0, v37
	v_mul_f32_e32 v0, 0x3e000000, v41
	v_mul_f32_e32 v48, v0, v4
	v_mul_f32_e32 v4, 0x3fb8aa3b, v53
	v_exp_f32_e32 v4, v4
	s_nop 0
	v_mul_f32_e32 v47, v0, v4
	v_sub_f32_e32 v4, v5, v1
	v_sub_f32_e32 v1, v1, v5
	v_mul_f32_e32 v1, 0x3fb8aa3b, v1
	v_exp_f32_e32 v1, v1
	v_mul_f32_e32 v4, 0x3fb8aa3b, v4
	v_exp_f32_e32 v4, v4
	v_mul_f32_e32 v45, v1, v50
	v_sub_f32_e32 v1, v53, v55
	v_mul_f32_e32 v1, 0x3fb8aa3b, v1
	v_exp_f32_e32 v1, v1
	v_mul_f32_e32 v46, v0, v4
	v_add_u32_e32 v4, 0x4118, v12
	ds_read2_b32 v[4:5], v4 offset1:1
	v_mul_f32_e32 v43, v0, v1
	v_sub_f32_e32 v0, v55, v53
	v_mul_f32_e32 v0, 0x3fb8aa3b, v0
	v_exp_f32_e32 v0, v0
	s_nop 0
	v_mul_f32_e32 v41, v0, v50
	ds_read2_b32 v[0:1], v12 offset0:6 offset1:7
	ds_read2_b32 v[50:51], v10 offset1:1
	s_waitcnt lgkmcnt(2)
	v_mul_f32_e32 v12, 0x3fb8aa3b, v4
	v_exp_f32_e32 v12, v12
	s_waitcnt lgkmcnt(1)
	v_mul_f32_e32 v10, 0x3fb8aa3b, v0
	v_sub_f32_e32 v52, v0, v2
	v_sub_f32_e32 v0, v2, v0
	v_mul_f32_e32 v0, 0x3fb8aa3b, v0
	v_exp_f32_e32 v0, v0
	v_mul_f32_e32 v52, 0x3fb8aa3b, v52
	v_exp_f32_e32 v10, v10
	v_exp_f32_e32 v52, v52
	v_mul_f32_e32 v53, v0, v24
	s_waitcnt lgkmcnt(0)
	v_sub_f32_e32 v0, v4, v50
	v_mul_f32_e32 v0, 0x3fb8aa3b, v0
	v_exp_f32_e32 v0, v0
	v_mul_f32_e32 v10, v49, v10
	v_mul_f32_e32 v12, v49, v12
	v_mul_f32_e32 v52, v49, v52
	v_mul_f32_e32 v49, v49, v0
	v_sub_f32_e32 v0, v50, v4
	v_mul_f32_e32 v0, 0x3fb8aa3b, v0
	v_exp_f32_e32 v0, v0
	v_mul_f32_e32 v2, 0x3fb8aa3b, v1
	v_exp_f32_e32 v2, v2
	v_mul_f32_e32 v4, v0, v24
	v_mul_f32_e32 v0, 0x3e000000, v16
	v_mul_f32_e32 v16, v0, v2
	v_mul_f32_e32 v2, 0x3fb8aa3b, v5
	v_exp_f32_e32 v2, v2
	s_nop 0
	v_mul_f32_e32 v24, v0, v2
	v_sub_f32_e32 v2, v1, v3
	v_sub_f32_e32 v1, v3, v1
	v_mul_f32_e32 v1, 0x3fb8aa3b, v1
	v_exp_f32_e32 v1, v1
	v_mul_f32_e32 v2, 0x3fb8aa3b, v2
	v_exp_f32_e32 v2, v2
	v_mul_f32_e32 v54, v1, v9
	v_sub_f32_e32 v1, v5, v51
	v_mul_f32_e32 v1, 0x3fb8aa3b, v1
	v_exp_f32_e32 v1, v1
	v_mul_f32_e32 v50, v0, v2
	v_mul_f32_e32 v55, v0, v1
	v_sub_f32_e32 v0, v51, v5
	v_mul_f32_e32 v0, 0x3fb8aa3b, v0
	v_exp_f32_e32 v0, v0
	s_nop 0
	v_mul_f32_e32 v5, v0, v9
	v_mul_lo_u32 v9, v170, s85
	v_cvt_pk_bf16_f32 v0, v23, v28
	v_cvt_pk_bf16_f32 v1, v32, v36
	v_cvt_pk_bf16_f32 v2, v44, v48
	v_cvt_pk_bf16_f32 v3, v10, v16
	v_add3_u32 v9, 0, v9, v176
	ds_write_b128 v9, v[0:3] offset:54272
	v_cvt_pk_bf16_f32 v0, v21, v27
	v_cvt_pk_bf16_f32 v1, v31, v35
	v_cvt_pk_bf16_f32 v2, v42, v47
	v_cvt_pk_bf16_f32 v3, v12, v24
	ds_write_b128 v9, v[0:3] offset:54400
	v_mul_lo_u32 v9, v170, s87
	v_cvt_pk_bf16_f32 v0, v19, v26
	v_cvt_pk_bf16_f32 v1, v30, v34
	v_cvt_pk_bf16_f32 v2, v40, v46
	v_cvt_pk_bf16_f32 v3, v52, v50
	v_add3_u32 v10, s86, v9, v176
	ds_write_b128 v10, v[0:3]
	v_cvt_pk_bf16_f32 v0, v18, v25
	v_cvt_pk_bf16_f32 v1, v29, v33
	v_cvt_pk_bf16_f32 v2, v39, v45
	v_cvt_pk_bf16_f32 v3, v53, v54
	v_add3_u32 v10, s88, v9, v176
	ds_write_b128 v10, v[0:3]
	v_cvt_pk_bf16_f32 v0, v17, v22
	v_cvt_pk_bf16_f32 v1, v14, v15
	v_cvt_pk_bf16_f32 v2, v38, v43
	v_cvt_pk_bf16_f32 v3, v49, v55
	v_add3_u32 v10, s89, v9, v176
	ds_write_b128 v10, v[0:3]
	v_cvt_pk_bf16_f32 v0, v13, v20
	v_cvt_pk_bf16_f32 v1, v6, v7
	v_cvt_pk_bf16_f32 v2, v37, v41
	v_cvt_pk_bf16_f32 v3, v4, v5
	v_add3_u32 v4, s52, v9, v176
	ds_write_b128 v4, v[0:3]
	v_lshl_add_u64 v[0:1], v[118:119], 0, s[8:9]
	v_mov_b32_e32 v9, v177
	v_lshl_add_u64 v[0:1], v[0:1], 0, v[8:9]
	v_lshl_add_u64 v[4:5], v[0:1], 0, s[0:1]
	v_add_co_u32_e64 v0, s[0:1], s92, v0
	v_lshlrev_b32_e32 v17, 1, v170
	s_nop 0
	v_addc_co_u32_e64 v1, s[0:1], 0, v1, s[0:1]
	s_waitcnt vmcnt(0)
	v_mov_b32_e32 v0, v224
	v_mov_b32_e32 v1, v225
	v_mov_b32_e32 v2, v226
	v_mov_b32_e32 v3, v227
	v_mov_b32_e32 v4, v228
	v_mov_b32_e32 v5, v229
	v_mov_b32_e32 v6, v230
	v_mov_b32_e32 v7, v231
	v_add3_u32 v11, s53, v17, v11
	s_lshl_b64 s[0:1], s[14:15], 18
	s_add_u32 s0, s56, s0
	s_addc_u32 s1, s57, s1
	s_or_b32 s2, s14, 1
	s_waitcnt vmcnt(1)
	v_lshlrev_b32_e32 v8, 16, v0
	v_and_b32_e32 v0, 0xffff0000, v0
	v_cvt_pk_bf16_f32 v8, v8, v177
	ds_write_b16 v11, v8
	v_cvt_pk_bf16_f32 v0, v0, v177
	v_lshlrev_b32_e32 v9, 16, v1
	ds_write_b16 v11, v0 offset:144
	v_cvt_pk_bf16_f32 v0, v9, v177
	v_and_b32_e32 v1, 0xffff0000, v1
	ds_write_b16 v11, v0 offset:288
	v_cvt_pk_bf16_f32 v0, v1, v177
	v_lshlrev_b32_e32 v10, 16, v2
	ds_write_b16 v11, v0 offset:432
	v_cvt_pk_bf16_f32 v0, v10, v177
	v_and_b32_e32 v2, 0xffff0000, v2
	ds_write_b16 v11, v0 offset:576
	v_cvt_pk_bf16_f32 v0, v2, v177
	v_lshlrev_b32_e32 v12, 16, v3
	ds_write_b16 v11, v0 offset:720
	v_cvt_pk_bf16_f32 v0, v12, v177
	v_and_b32_e32 v3, 0xffff0000, v3
	ds_write_b16 v11, v0 offset:864
	v_cvt_pk_bf16_f32 v0, v3, v177
	s_waitcnt vmcnt(0)
	v_lshlrev_b32_e32 v13, 16, v4
	ds_write_b16 v11, v0 offset:1008
	v_cvt_pk_bf16_f32 v0, v13, v177
	v_and_b32_e32 v4, 0xffff0000, v4
	ds_write_b16 v11, v0 offset:1152
	v_cvt_pk_bf16_f32 v0, v4, v177
	v_lshlrev_b32_e32 v14, 16, v5
	ds_write_b16 v11, v0 offset:1296
	v_cvt_pk_bf16_f32 v0, v14, v177
	v_and_b32_e32 v5, 0xffff0000, v5
	ds_write_b16 v11, v0 offset:1440
	v_cvt_pk_bf16_f32 v0, v5, v177
	v_lshlrev_b32_e32 v15, 16, v6
	ds_write_b16 v11, v0 offset:1584
	v_cvt_pk_bf16_f32 v0, v15, v177
	v_and_b32_e32 v6, 0xffff0000, v6
	ds_write_b16 v11, v0 offset:1728
	v_cvt_pk_bf16_f32 v0, v6, v177
	v_lshlrev_b32_e32 v16, 16, v7
	ds_write_b16 v11, v0 offset:1872
	v_cvt_pk_bf16_f32 v0, v16, v177
	v_and_b32_e32 v7, 0xffff0000, v7
	ds_write_b16 v11, v0 offset:2016
	v_cvt_pk_bf16_f32 v0, v7, v177
	ds_write_b16 v11, v0 offset:2160
	v_lshlrev_b32_e32 v0, 11, v171
	v_and_b32_e32 v2, 0x7800, v0
	v_mov_b32_e32 v3, v177
	v_lshl_add_u64 v[0:1], s[0:1], 0, v[2:3]
	s_lshl_b64 s[0:1], s[2:3], 18
	s_add_u32 s0, s56, s0
	s_addc_u32 s1, s57, s1
	v_lshl_add_u64 v[2:3], s[0:1], 0, v[2:3]
	s_cbranch_vccz .LBB0_659
	v_readlane_b32 s68, v254, 16
	v_readlane_b32 s69, v254, 17
	s_sub_i32 s70, s61, 64
	s_lshl_b32 s70, s70, 3
	s_or_b32 s70, s70, s55
	s_mov_b32 s71, 0
	s_lshl_b64 s[70:71], s[70:71], 16
	s_add_u32 s68, s68, s70
	s_addc_u32 s69, s69, s71
	s_add_u32 s70, s68, 0x8000
	s_addc_u32 s71, s69, 0
	v_lshlrev_b32_e32 v186, 4, v171
	global_load_dwordx4 v[132:135], v186, s[68:69]
	global_load_dwordx4 v[128:131], v186, s[70:71]
	v_add_u32_e32 v187, 0x2000, v186
	global_load_dwordx4 v[140:143], v187, s[68:69]
	global_load_dwordx4 v[136:139], v187, s[70:71]
	v_add_u32_e32 v187, 0x4000, v186
	global_load_dwordx4 v[148:151], v187, s[68:69]
	global_load_dwordx4 v[144:147], v187, s[70:71]
	v_add_u32_e32 v187, 0x6000, v186
	global_load_dwordx4 v[156:159], v187, s[68:69]
	global_load_dwordx4 v[152:155], v187, s[70:71]
	v_ashrrev_i32_e32 v117, 31, v116
	s_branch .LBB0_643
	v_ashrrev_i32_e32 v4, 4, v171
	v_ashrrev_i32_e32 v5, 31, v4
	v_lshlrev_b64 v[4:5], 2, v[4:5]
	v_lshl_add_u64 v[6:7], v[0:1], 0, v[4:5]
	v_lshl_add_u64 v[4:5], v[2:3], 0, v[4:5]
	global_load_dword v132, v[6:7], off
	global_load_dword v133, v[6:7], off offset:512
	global_load_dword v134, v[6:7], off offset:1024
	global_load_dword v135, v[6:7], off offset:1536
	global_load_dword v128, v[4:5], off
	global_load_dword v129, v[4:5], off offset:512
	global_load_dword v130, v[4:5], off offset:1024
	global_load_dword v131, v[4:5], off offset:1536
	v_cndmask_b32_e64 v4, 0, 1, s[24:25]
	v_cmp_ne_u32_e64 s[0:1], 1, v4
	s_andn2_b64 vcc, exec, s[24:25]
	s_cbranch_vccz .LBB0_660
